# P6 epilogues hand-written: mid (all 16 gate loads at once, counted waits) and final (gate loads up front, rotated row groups, one LDS transpose per row group)
# speedup vs baseline: 1.0061x; 1.0009x over previous
; #define PG8_LAS __attribute__((address_space(3)))
; __device__ __forceinline__ u32x4 pack8(const f32x4 a, const f32x4 b) { u32x4 w; w.x = cvt_pk_bf16(a[0], a[1]); w.y = cvt_pk_bf16(a[2], a[3]); w.z = cvt_pk_bf16(b[0], b[1]); w.w = cvt_pk_bf16(b[2], b[3]); return w; }
; #define SA_LOAD(D, r_) do { const int rw_ = u.pm * BM + ((r_) >> 2) * HALF + wr * 64 + ((r_) & 3) * 16 + fr; const size_t ro_ = (size_t)(rw_ >> 1) * (2 * DM) + (u.pn * 8 + wc * 2) * 64 + (rw_ & 1) * 32 + fq * 8; D[0] = *(const u32x4*)(sa + ro_); D[1] = *(const u32x4*)(sa + ro_ + 64); } while (0)
; __device__ __forceinline__ void store_lines(PG8_LAS unsigned char* stg, const u32x4 P0, const u32x4 P1, int fr, int fq, bf16_t* seg0, int pitch) {
;     const int ln = fq * 16 + fr;
; #pragma unroll
;     for (int h = 0; h < 2; ++h) {
;         if ((fr >> 3) == h) { *(PG8_LAS u32x4*)(stg + (fr & 7) * 128 + fq * 16) = P0; *(PG8_LAS u32x4*)(stg + (fr & 7) * 128 + 64 + fq * 16) = P1; }
;         __builtin_amdgcn_wave_barrier(); asm volatile("" ::: "memory");
;         const u32x4 v = *(const PG8_LAS u32x4*)(stg + ln * 16);
;         __builtin_amdgcn_wave_barrier(); asm volatile("" ::: "memory");
;         *(u32x4*)(seg0 + (size_t)(8 * h + (ln >> 3)) * pitch + (ln & 7) * 8) = v; }
;     __device__ __forceinline__ void operator()(const f32x4 (&acc)[2][2][4][2], const Unit& u, int wr, int wc, int fr, int fq) const {
;         asm volatile("" : "+v"(fr), "+v"(fq));
;         const int col0 = u.pn * BM + wc * 64 + fq * 8;
;         u32x4 cg[2], ng[2];
;     ...
;         SA_LOAD(cg, 0);
; #pragma unroll
;         for (int r = 0; r < 8; ++r) { const int ai = r >> 2, m = r & 3; const int row = EPI_ROW;
;             if (r < 7) SA_LOAD(ng, r + 1);
;             u32x4 pm_[2];
; #pragma unroll
;             for (int bj = 0; bj < 2; ++bj) { f32x4 g0, g1; unpack8(cg[bj], g0, g1); pm_[bj] = pack8(g0 * acc[ai][bj][m][0], g1 * acc[ai][bj][m][1]); }
;             store_lines(stg + (wr * 4 + wc) * 1024, pm_[0], pm_[1], fr, fq, mg + (size_t)(row - fr) * DM + u.pn * BM + wc * 64, DM);
;             cg[0] = ng[0]; cg[1] = ng[1]; }
.LBB0_726:
	s_cmp_lg_u32 s38, 0
	s_cselect_b64 s[28:29], -1, 0
	s_and_b64 vcc, exec, s[28:29]
	s_cbranch_vccz .LBB0_766
	s_lshl_b32 s23, s34, 8
	s_add_i32 s23, s23, s57
	s_lshl_b32 s23, s23, 11
	s_lshl_b32 s21, s30, 9
	s_or_b32 s21, s21, s61
	s_lshl_b32 s21, s21, 1
	s_add_u32 s21, s21, s23
	s_add_u32 s0, s10, s21
	s_addc_u32 s1, s11, 0
	s_lshl_b32 s21, s30, 8
	s_or_b32 s21, s21, s60
	s_lshl_b32 s21, s21, 1
	s_add_u32 s21, s21, s23
	s_add_u32 s36, s55, s21
	s_addc_u32 s37, s56, 0
	v_lshrrev_b32_e32 v174, 1, v1
	v_lshlrev_b32_e32 v174, 12, v174
	v_and_b32_e32 v134, 1, v1
	v_lshl_add_u32 v174, v134, 6, v174
	v_lshl_add_u32 v174, v176, 4, v174
	s_mov_b64 s[98:99], s[0:1]
	global_load_dwordx4 v[180:183], v174, s[98:99]
	global_load_dwordx4 v[184:187], v174, s[98:99] offset:128
	s_add_u32 s98, s0, 0x8000
	s_addc_u32 s99, s1, 0
	global_load_dwordx4 v[188:191], v174, s[98:99]
	global_load_dwordx4 v[192:195], v174, s[98:99] offset:128
	s_add_u32 s98, s0, 0x10000
	s_addc_u32 s99, s1, 0
	global_load_dwordx4 v[196:199], v174, s[98:99]
	global_load_dwordx4 v[200:203], v174, s[98:99] offset:128
	s_add_u32 s98, s0, 0x18000
	s_addc_u32 s99, s1, 0
	global_load_dwordx4 v[204:207], v174, s[98:99]
	global_load_dwordx4 v[208:211], v174, s[98:99] offset:128
	s_add_u32 s98, s0, 0x40000
	s_addc_u32 s99, s1, 0
	global_load_dwordx4 v[212:215], v174, s[98:99]
	global_load_dwordx4 v[216:219], v174, s[98:99] offset:128
	s_add_u32 s98, s0, 0x48000
	s_addc_u32 s99, s1, 0
	global_load_dwordx4 v[222:225], v174, s[98:99]
	global_load_dwordx4 v[226:229], v174, s[98:99] offset:128
	s_add_u32 s98, s0, 0x50000
	s_addc_u32 s99, s1, 0
	global_load_dwordx4 v[230:233], v174, s[98:99]
	global_load_dwordx4 v[234:237], v174, s[98:99] offset:128
	s_add_u32 s98, s0, 0x58000
	s_addc_u32 s99, s1, 0
	global_load_dwordx4 v[238:241], v174, s[98:99]
	global_load_dwordx4 v[242:245], v174, s[98:99] offset:128
	s_lshl_b32 s21, s57, 7
	s_lshl_b32 s23, s60, 5
	s_add_i32 s21, s21, s23
	s_add_i32 s21, s21, 0x20000
	v_lshlrev_b32_e32 v2, 7, v1
	v_lshl_add_u32 v2, v176, 4, v2
	v_add_u32_e32 v2, s21, v2
	v_lshl_add_u32 v4, v220, 4, s21
	v_lshrrev_b32_e32 v175, 3, v220
	v_lshlrev_b32_e32 v175, 11, v175
	v_and_b32_e32 v134, 7, v220
	v_lshl_add_u32 v175, v134, 4, v175
	s_lshr_b32 s40, s57, 4
	s_lshr_b32 s41, s60, 6
	s_add_u32 s40, s40, s41
	s_mov_b32 s41, 8
	s_waitcnt vmcnt(0)
	s_cmp_eq_u32 s40, 1
	s_cbranch_scc1 .Lp6f_rg1
	s_cmp_eq_u32 s40, 2
	s_cbranch_scc1 .Lp6f_rg2
	s_cmp_eq_u32 s40, 3
	s_cbranch_scc1 .Lp6f_rg3
	s_cmp_eq_u32 s40, 4
	s_cbranch_scc1 .Lp6f_rg4
	s_cmp_eq_u32 s40, 5
	s_cbranch_scc1 .Lp6f_rg5
	s_cmp_eq_u32 s40, 6
	s_cbranch_scc1 .Lp6f_rg6
	s_cmp_eq_u32 s40, 7
	s_cbranch_scc1 .Lp6f_rg7
.Lp6f_rg0:
	s_add_u32 s98, s36, 0x0
	s_addc_u32 s99, s37, 0
	s_add_u32 s100, s98, 0x4000
	s_addc_u32 s101, s99, 0
	v_lshlrev_b32_e32 v134, 16, v180
	v_and_b32_e32 v135, 0xffff0000, v180
	v_lshlrev_b32_e32 v136, 16, v181
	v_and_b32_e32 v137, 0xffff0000, v181
	v_lshlrev_b32_e32 v138, 16, v182
	v_and_b32_e32 v139, 0xffff0000, v182
	v_lshlrev_b32_e32 v140, 16, v183
	v_and_b32_e32 v141, 0xffff0000, v183
	v_lshlrev_b32_e32 v142, 16, v184
	v_and_b32_e32 v143, 0xffff0000, v184
	v_lshlrev_b32_e32 v144, 16, v185
	v_and_b32_e32 v145, 0xffff0000, v185
	v_lshlrev_b32_e32 v146, 16, v186
	v_and_b32_e32 v147, 0xffff0000, v186
	v_lshlrev_b32_e32 v148, 16, v187
	v_and_b32_e32 v149, 0xffff0000, v187
	v_pk_mul_f32 v[134:135], v[130:131], v[134:135]
	v_pk_mul_f32 v[136:137], v[132:133], v[136:137]
	v_pk_mul_f32 v[138:139], v[126:127], v[138:139]
	v_pk_mul_f32 v[140:141], v[128:129], v[140:141]
	v_pk_mul_f32 v[142:143], v[98:99], v[142:143]
	v_pk_mul_f32 v[144:145], v[100:101], v[144:145]
	v_pk_mul_f32 v[146:147], v[94:95], v[146:147]
	v_pk_mul_f32 v[148:149], v[96:97], v[148:149]
	v_cvt_pk_bf16_f32 v246, v134, v135
	v_cvt_pk_bf16_f32 v247, v136, v137
	v_cvt_pk_bf16_f32 v248, v138, v139
	v_cvt_pk_bf16_f32 v249, v140, v141
	v_cvt_pk_bf16_f32 v250, v142, v143
	v_cvt_pk_bf16_f32 v251, v144, v145
	v_cvt_pk_bf16_f32 v252, v146, v147
	v_cvt_pk_bf16_f32 v253, v148, v149
	ds_write_b128 v2, v[246:249]
	ds_write_b128 v2, v[250:253] offset:64
	ds_read_b128 v[150:153], v4
	ds_read_b128 v[170:173], v4 offset:1024
	s_waitcnt lgkmcnt(1)
	global_store_dwordx4 v175, v[150:153], s[98:99]
	s_waitcnt lgkmcnt(0)
	global_store_dwordx4 v175, v[170:173], s[100:101]
	s_add_i32 s41, s41, -1
	s_cmp_eq_u32 s41, 0
	s_cbranch_scc1 .LBB0_761
.Lp6f_rg1:
	s_add_u32 s98, s36, 0x8000
	s_addc_u32 s99, s37, 0
	s_add_u32 s100, s98, 0x4000
	s_addc_u32 s101, s99, 0
	v_lshlrev_b32_e32 v134, 16, v188
	v_and_b32_e32 v135, 0xffff0000, v188
	v_lshlrev_b32_e32 v136, 16, v189
	v_and_b32_e32 v137, 0xffff0000, v189
	v_lshlrev_b32_e32 v138, 16, v190
	v_and_b32_e32 v139, 0xffff0000, v190
	v_lshlrev_b32_e32 v140, 16, v191
	v_and_b32_e32 v141, 0xffff0000, v191
	v_lshlrev_b32_e32 v142, 16, v192
	v_and_b32_e32 v143, 0xffff0000, v192
	v_lshlrev_b32_e32 v144, 16, v193
	v_and_b32_e32 v145, 0xffff0000, v193
	v_lshlrev_b32_e32 v146, 16, v194
	v_and_b32_e32 v147, 0xffff0000, v194
	v_lshlrev_b32_e32 v148, 16, v195
	v_and_b32_e32 v149, 0xffff0000, v195
	v_pk_mul_f32 v[134:135], v[122:123], v[134:135]
	v_pk_mul_f32 v[136:137], v[124:125], v[136:137]
	v_pk_mul_f32 v[138:139], v[118:119], v[138:139]
	v_pk_mul_f32 v[140:141], v[120:121], v[140:141]
	v_pk_mul_f32 v[142:143], v[90:91], v[142:143]
	v_pk_mul_f32 v[144:145], v[92:93], v[144:145]
	v_pk_mul_f32 v[146:147], v[86:87], v[146:147]
	v_pk_mul_f32 v[148:149], v[88:89], v[148:149]
	v_cvt_pk_bf16_f32 v246, v134, v135
	v_cvt_pk_bf16_f32 v247, v136, v137
	v_cvt_pk_bf16_f32 v248, v138, v139
	v_cvt_pk_bf16_f32 v249, v140, v141
	v_cvt_pk_bf16_f32 v250, v142, v143
	v_cvt_pk_bf16_f32 v251, v144, v145
	v_cvt_pk_bf16_f32 v252, v146, v147
	v_cvt_pk_bf16_f32 v253, v148, v149
	ds_write_b128 v2, v[246:249]
	ds_write_b128 v2, v[250:253] offset:64
	ds_read_b128 v[150:153], v4
	ds_read_b128 v[170:173], v4 offset:1024
	s_waitcnt lgkmcnt(1)
	global_store_dwordx4 v175, v[150:153], s[98:99]
	s_waitcnt lgkmcnt(0)
	global_store_dwordx4 v175, v[170:173], s[100:101]
	s_add_i32 s41, s41, -1
	s_cmp_eq_u32 s41, 0
	s_cbranch_scc1 .LBB0_761
; #define PG8_LAS __attribute__((address_space(3)))
; __device__ __forceinline__ u32x4 pack8(const f32x4 a, const f32x4 b) { u32x4 w; w.x = cvt_pk_bf16(a[0], a[1]); w.y = cvt_pk_bf16(a[2], a[3]); w.z = cvt_pk_bf16(b[0], b[1]); w.w = cvt_pk_bf16(b[2], b[3]); return w; }
; #define SA_LOAD(D, r_) do { const int rw_ = u.pm * BM + ((r_) >> 2) * HALF + wr * 64 + ((r_) & 3) * 16 + fr; const size_t ro_ = (size_t)(rw_ >> 1) * (2 * DM) + (u.pn * 8 + wc * 2) * 64 + (rw_ & 1) * 32 + fq * 8; D[0] = *(const u32x4*)(sa + ro_); D[1] = *(const u32x4*)(sa + ro_ + 64); } while (0)
; __device__ __forceinline__ void store_lines(PG8_LAS unsigned char* stg, const u32x4 P0, const u32x4 P1, int fr, int fq, bf16_t* seg0, int pitch) {
;     const int ln = fq * 16 + fr;
; #pragma unroll
;     for (int h = 0; h < 2; ++h) {
;         if ((fr >> 3) == h) { *(PG8_LAS u32x4*)(stg + (fr & 7) * 128 + fq * 16) = P0; *(PG8_LAS u32x4*)(stg + (fr & 7) * 128 + 64 + fq * 16) = P1; }
;         __builtin_amdgcn_wave_barrier(); asm volatile("" ::: "memory");
;         const u32x4 v = *(const PG8_LAS u32x4*)(stg + ln * 16);
;         __builtin_amdgcn_wave_barrier(); asm volatile("" ::: "memory");
;         *(u32x4*)(seg0 + (size_t)(8 * h + (ln >> 3)) * pitch + (ln & 7) * 8) = v; }
;     __device__ __forceinline__ void operator()(const f32x4 (&acc)[2][2][4][2], const Unit& u, int wr, int wc, int fr, int fq) const {
;     ...
;         for (int r = 0; r < 8; ++r) { const int ai = r >> 2, m = r & 3; const int row = EPI_ROW;
;             if (r < 7) SA_LOAD(ng, r + 1);
;             u32x4 pm_[2];
; #pragma unroll
;             for (int bj = 0; bj < 2; ++bj) { f32x4 g0, g1; unpack8(cg[bj], g0, g1); pm_[bj] = pack8(g0 * acc[ai][bj][m][0], g1 * acc[ai][bj][m][1]); }
;             store_lines(stg + (wr * 4 + wc) * 1024, pm_[0], pm_[1], fr, fq, mg + (size_t)(row - fr) * DM + u.pn * BM + wc * 64, DM);
;             cg[0] = ng[0]; cg[1] = ng[1]; }
.Lp6f_rg2:
	s_add_u32 s98, s36, 0x10000
	s_addc_u32 s99, s37, 0
	s_add_u32 s100, s98, 0x4000
	s_addc_u32 s101, s99, 0
	v_lshlrev_b32_e32 v134, 16, v196
	v_and_b32_e32 v135, 0xffff0000, v196
	v_lshlrev_b32_e32 v136, 16, v197
	v_and_b32_e32 v137, 0xffff0000, v197
	v_lshlrev_b32_e32 v138, 16, v198
	v_and_b32_e32 v139, 0xffff0000, v198
	v_lshlrev_b32_e32 v140, 16, v199
	v_and_b32_e32 v141, 0xffff0000, v199
	v_lshlrev_b32_e32 v142, 16, v200
	v_and_b32_e32 v143, 0xffff0000, v200
	v_lshlrev_b32_e32 v144, 16, v201
	v_and_b32_e32 v145, 0xffff0000, v201
	v_lshlrev_b32_e32 v146, 16, v202
	v_and_b32_e32 v147, 0xffff0000, v202
	v_lshlrev_b32_e32 v148, 16, v203
	v_and_b32_e32 v149, 0xffff0000, v203
	v_pk_mul_f32 v[134:135], v[114:115], v[134:135]
	v_pk_mul_f32 v[136:137], v[116:117], v[136:137]
	v_pk_mul_f32 v[138:139], v[110:111], v[138:139]
	v_pk_mul_f32 v[140:141], v[112:113], v[140:141]
	v_pk_mul_f32 v[142:143], v[82:83], v[142:143]
	v_pk_mul_f32 v[144:145], v[84:85], v[144:145]
	v_pk_mul_f32 v[146:147], v[78:79], v[146:147]
	v_pk_mul_f32 v[148:149], v[80:81], v[148:149]
	v_cvt_pk_bf16_f32 v246, v134, v135
	v_cvt_pk_bf16_f32 v247, v136, v137
	v_cvt_pk_bf16_f32 v248, v138, v139
	v_cvt_pk_bf16_f32 v249, v140, v141
	v_cvt_pk_bf16_f32 v250, v142, v143
	v_cvt_pk_bf16_f32 v251, v144, v145
	v_cvt_pk_bf16_f32 v252, v146, v147
	v_cvt_pk_bf16_f32 v253, v148, v149
	ds_write_b128 v2, v[246:249]
	ds_write_b128 v2, v[250:253] offset:64
	ds_read_b128 v[150:153], v4
	ds_read_b128 v[170:173], v4 offset:1024
	s_waitcnt lgkmcnt(1)
	global_store_dwordx4 v175, v[150:153], s[98:99]
	s_waitcnt lgkmcnt(0)
	global_store_dwordx4 v175, v[170:173], s[100:101]
	s_add_i32 s41, s41, -1
	s_cmp_eq_u32 s41, 0
	s_cbranch_scc1 .LBB0_761
.Lp6f_rg3:
	s_add_u32 s98, s36, 0x18000
	s_addc_u32 s99, s37, 0
	s_add_u32 s100, s98, 0x4000
	s_addc_u32 s101, s99, 0
	v_lshlrev_b32_e32 v134, 16, v204
	v_and_b32_e32 v135, 0xffff0000, v204
	v_lshlrev_b32_e32 v136, 16, v205
	v_and_b32_e32 v137, 0xffff0000, v205
	v_lshlrev_b32_e32 v138, 16, v206
	v_and_b32_e32 v139, 0xffff0000, v206
	v_lshlrev_b32_e32 v140, 16, v207
	v_and_b32_e32 v141, 0xffff0000, v207
	v_lshlrev_b32_e32 v142, 16, v208
	v_and_b32_e32 v143, 0xffff0000, v208
	v_lshlrev_b32_e32 v144, 16, v209
	v_and_b32_e32 v145, 0xffff0000, v209
	v_lshlrev_b32_e32 v146, 16, v210
	v_and_b32_e32 v147, 0xffff0000, v210
	v_lshlrev_b32_e32 v148, 16, v211
	v_and_b32_e32 v149, 0xffff0000, v211
	v_pk_mul_f32 v[134:135], v[106:107], v[134:135]
	v_pk_mul_f32 v[136:137], v[108:109], v[136:137]
	v_pk_mul_f32 v[138:139], v[102:103], v[138:139]
	v_pk_mul_f32 v[140:141], v[104:105], v[140:141]
	v_pk_mul_f32 v[142:143], v[74:75], v[142:143]
	v_pk_mul_f32 v[144:145], v[76:77], v[144:145]
	v_pk_mul_f32 v[146:147], v[70:71], v[146:147]
	v_pk_mul_f32 v[148:149], v[72:73], v[148:149]
	v_cvt_pk_bf16_f32 v246, v134, v135
	v_cvt_pk_bf16_f32 v247, v136, v137
	v_cvt_pk_bf16_f32 v248, v138, v139
	v_cvt_pk_bf16_f32 v249, v140, v141
	v_cvt_pk_bf16_f32 v250, v142, v143
	v_cvt_pk_bf16_f32 v251, v144, v145
	v_cvt_pk_bf16_f32 v252, v146, v147
	v_cvt_pk_bf16_f32 v253, v148, v149
	ds_write_b128 v2, v[246:249]
	ds_write_b128 v2, v[250:253] offset:64
	ds_read_b128 v[150:153], v4
	ds_read_b128 v[170:173], v4 offset:1024
	s_waitcnt lgkmcnt(1)
	global_store_dwordx4 v175, v[150:153], s[98:99]
	s_waitcnt lgkmcnt(0)
	global_store_dwordx4 v175, v[170:173], s[100:101]
	s_add_i32 s41, s41, -1
	s_cmp_eq_u32 s41, 0
	s_cbranch_scc1 .LBB0_761
.Lp6f_rg4:
	s_add_u32 s98, s36, 0x40000
	s_addc_u32 s99, s37, 0
	s_add_u32 s100, s98, 0x4000
	s_addc_u32 s101, s99, 0
	v_lshlrev_b32_e32 v134, 16, v212
	v_and_b32_e32 v135, 0xffff0000, v212
	v_lshlrev_b32_e32 v136, 16, v213
	v_and_b32_e32 v137, 0xffff0000, v213
	v_lshlrev_b32_e32 v138, 16, v214
	v_and_b32_e32 v139, 0xffff0000, v214
	v_lshlrev_b32_e32 v140, 16, v215
	v_and_b32_e32 v141, 0xffff0000, v215
	v_lshlrev_b32_e32 v142, 16, v216
	v_and_b32_e32 v143, 0xffff0000, v216
	v_lshlrev_b32_e32 v144, 16, v217
	v_and_b32_e32 v145, 0xffff0000, v217
	v_lshlrev_b32_e32 v146, 16, v218
	v_and_b32_e32 v147, 0xffff0000, v218
	v_lshlrev_b32_e32 v148, 16, v219
	v_and_b32_e32 v149, 0xffff0000, v219
	v_pk_mul_f32 v[134:135], v[66:67], v[134:135]
	v_pk_mul_f32 v[136:137], v[68:69], v[136:137]
	v_pk_mul_f32 v[138:139], v[62:63], v[138:139]
	v_pk_mul_f32 v[140:141], v[64:65], v[140:141]
	v_pk_mul_f32 v[142:143], v[34:35], v[142:143]
	v_pk_mul_f32 v[144:145], v[36:37], v[144:145]
	v_pk_mul_f32 v[146:147], v[30:31], v[146:147]
	v_pk_mul_f32 v[148:149], v[32:33], v[148:149]
	v_cvt_pk_bf16_f32 v246, v134, v135
	v_cvt_pk_bf16_f32 v247, v136, v137
	v_cvt_pk_bf16_f32 v248, v138, v139
	v_cvt_pk_bf16_f32 v249, v140, v141
	v_cvt_pk_bf16_f32 v250, v142, v143
	v_cvt_pk_bf16_f32 v251, v144, v145
	v_cvt_pk_bf16_f32 v252, v146, v147
	v_cvt_pk_bf16_f32 v253, v148, v149
	ds_write_b128 v2, v[246:249]
	ds_write_b128 v2, v[250:253] offset:64
	ds_read_b128 v[150:153], v4
	ds_read_b128 v[170:173], v4 offset:1024
	s_waitcnt lgkmcnt(1)
	global_store_dwordx4 v175, v[150:153], s[98:99]
	s_waitcnt lgkmcnt(0)
	global_store_dwordx4 v175, v[170:173], s[100:101]
	s_add_i32 s41, s41, -1
	s_cmp_eq_u32 s41, 0
	s_cbranch_scc1 .LBB0_761
; #define PG8_LAS __attribute__((address_space(3)))
; __device__ __forceinline__ u32x4 pack8(const f32x4 a, const f32x4 b) { u32x4 w; w.x = cvt_pk_bf16(a[0], a[1]); w.y = cvt_pk_bf16(a[2], a[3]); w.z = cvt_pk_bf16(b[0], b[1]); w.w = cvt_pk_bf16(b[2], b[3]); return w; }
; #define SA_LOAD(D, r_) do { const int rw_ = u.pm * BM + ((r_) >> 2) * HALF + wr * 64 + ((r_) & 3) * 16 + fr; const size_t ro_ = (size_t)(rw_ >> 1) * (2 * DM) + (u.pn * 8 + wc * 2) * 64 + (rw_ & 1) * 32 + fq * 8; D[0] = *(const u32x4*)(sa + ro_); D[1] = *(const u32x4*)(sa + ro_ + 64); } while (0)
; __device__ __forceinline__ void store_lines(PG8_LAS unsigned char* stg, const u32x4 P0, const u32x4 P1, int fr, int fq, bf16_t* seg0, int pitch) {
;     const int ln = fq * 16 + fr;
; #pragma unroll
;     for (int h = 0; h < 2; ++h) {
;         if ((fr >> 3) == h) { *(PG8_LAS u32x4*)(stg + (fr & 7) * 128 + fq * 16) = P0; *(PG8_LAS u32x4*)(stg + (fr & 7) * 128 + 64 + fq * 16) = P1; }
;         __builtin_amdgcn_wave_barrier(); asm volatile("" ::: "memory");
;         const u32x4 v = *(const PG8_LAS u32x4*)(stg + ln * 16);
;         __builtin_amdgcn_wave_barrier(); asm volatile("" ::: "memory");
;         *(u32x4*)(seg0 + (size_t)(8 * h + (ln >> 3)) * pitch + (ln & 7) * 8) = v; }
;     __device__ __forceinline__ void operator()(const f32x4 (&acc)[2][2][4][2], const Unit& u, int wr, int wc, int fr, int fq) const {
;     ...
;         for (int r = 0; r < 8; ++r) { const int ai = r >> 2, m = r & 3; const int row = EPI_ROW;
;             if (r < 7) SA_LOAD(ng, r + 1);
;             u32x4 pm_[2];
; #pragma unroll
;             for (int bj = 0; bj < 2; ++bj) { f32x4 g0, g1; unpack8(cg[bj], g0, g1); pm_[bj] = pack8(g0 * acc[ai][bj][m][0], g1 * acc[ai][bj][m][1]); }
;             store_lines(stg + (wr * 4 + wc) * 1024, pm_[0], pm_[1], fr, fq, mg + (size_t)(row - fr) * DM + u.pn * BM + wc * 64, DM);
;             cg[0] = ng[0]; cg[1] = ng[1]; }
.Lp6f_rg5:
	s_add_u32 s98, s36, 0x48000
	s_addc_u32 s99, s37, 0
	s_add_u32 s100, s98, 0x4000
	s_addc_u32 s101, s99, 0
	v_lshlrev_b32_e32 v134, 16, v222
	v_and_b32_e32 v135, 0xffff0000, v222
	v_lshlrev_b32_e32 v136, 16, v223
	v_and_b32_e32 v137, 0xffff0000, v223
	v_lshlrev_b32_e32 v138, 16, v224
	v_and_b32_e32 v139, 0xffff0000, v224
	v_lshlrev_b32_e32 v140, 16, v225
	v_and_b32_e32 v141, 0xffff0000, v225
	v_lshlrev_b32_e32 v142, 16, v226
	v_and_b32_e32 v143, 0xffff0000, v226
	v_lshlrev_b32_e32 v144, 16, v227
	v_and_b32_e32 v145, 0xffff0000, v227
	v_lshlrev_b32_e32 v146, 16, v228
	v_and_b32_e32 v147, 0xffff0000, v228
	v_lshlrev_b32_e32 v148, 16, v229
	v_and_b32_e32 v149, 0xffff0000, v229
	v_pk_mul_f32 v[134:135], v[58:59], v[134:135]
	v_pk_mul_f32 v[136:137], v[60:61], v[136:137]
	v_pk_mul_f32 v[138:139], v[54:55], v[138:139]
	v_pk_mul_f32 v[140:141], v[56:57], v[140:141]
	v_pk_mul_f32 v[142:143], v[26:27], v[142:143]
	v_pk_mul_f32 v[144:145], v[28:29], v[144:145]
	v_pk_mul_f32 v[146:147], v[22:23], v[146:147]
	v_pk_mul_f32 v[148:149], v[24:25], v[148:149]
	v_cvt_pk_bf16_f32 v246, v134, v135
	v_cvt_pk_bf16_f32 v247, v136, v137
	v_cvt_pk_bf16_f32 v248, v138, v139
	v_cvt_pk_bf16_f32 v249, v140, v141
	v_cvt_pk_bf16_f32 v250, v142, v143
	v_cvt_pk_bf16_f32 v251, v144, v145
	v_cvt_pk_bf16_f32 v252, v146, v147
	v_cvt_pk_bf16_f32 v253, v148, v149
	ds_write_b128 v2, v[246:249]
	ds_write_b128 v2, v[250:253] offset:64
	ds_read_b128 v[150:153], v4
	ds_read_b128 v[170:173], v4 offset:1024
	s_waitcnt lgkmcnt(1)
	global_store_dwordx4 v175, v[150:153], s[98:99]
	s_waitcnt lgkmcnt(0)
	global_store_dwordx4 v175, v[170:173], s[100:101]
	s_add_i32 s41, s41, -1
	s_cmp_eq_u32 s41, 0
	s_cbranch_scc1 .LBB0_761
.Lp6f_rg6:
	s_add_u32 s98, s36, 0x50000
	s_addc_u32 s99, s37, 0
	s_add_u32 s100, s98, 0x4000
	s_addc_u32 s101, s99, 0
	v_lshlrev_b32_e32 v134, 16, v230
	v_and_b32_e32 v135, 0xffff0000, v230
	v_lshlrev_b32_e32 v136, 16, v231
	v_and_b32_e32 v137, 0xffff0000, v231
	v_lshlrev_b32_e32 v138, 16, v232
	v_and_b32_e32 v139, 0xffff0000, v232
	v_lshlrev_b32_e32 v140, 16, v233
	v_and_b32_e32 v141, 0xffff0000, v233
	v_lshlrev_b32_e32 v142, 16, v234
	v_and_b32_e32 v143, 0xffff0000, v234
	v_lshlrev_b32_e32 v144, 16, v235
	v_and_b32_e32 v145, 0xffff0000, v235
	v_lshlrev_b32_e32 v146, 16, v236
	v_and_b32_e32 v147, 0xffff0000, v236
	v_lshlrev_b32_e32 v148, 16, v237
	v_and_b32_e32 v149, 0xffff0000, v237
	v_pk_mul_f32 v[134:135], v[50:51], v[134:135]
	v_pk_mul_f32 v[136:137], v[52:53], v[136:137]
	v_pk_mul_f32 v[138:139], v[46:47], v[138:139]
	v_pk_mul_f32 v[140:141], v[48:49], v[140:141]
	v_pk_mul_f32 v[142:143], v[18:19], v[142:143]
	v_pk_mul_f32 v[144:145], v[20:21], v[144:145]
	v_pk_mul_f32 v[146:147], v[14:15], v[146:147]
	v_pk_mul_f32 v[148:149], v[16:17], v[148:149]
	v_cvt_pk_bf16_f32 v246, v134, v135
	v_cvt_pk_bf16_f32 v247, v136, v137
	v_cvt_pk_bf16_f32 v248, v138, v139
	v_cvt_pk_bf16_f32 v249, v140, v141
	v_cvt_pk_bf16_f32 v250, v142, v143
	v_cvt_pk_bf16_f32 v251, v144, v145
	v_cvt_pk_bf16_f32 v252, v146, v147
	v_cvt_pk_bf16_f32 v253, v148, v149
	ds_write_b128 v2, v[246:249]
	ds_write_b128 v2, v[250:253] offset:64
	ds_read_b128 v[150:153], v4
	ds_read_b128 v[170:173], v4 offset:1024
	s_waitcnt lgkmcnt(1)
	global_store_dwordx4 v175, v[150:153], s[98:99]
	s_waitcnt lgkmcnt(0)
	global_store_dwordx4 v175, v[170:173], s[100:101]
	s_add_i32 s41, s41, -1
	s_cmp_eq_u32 s41, 0
	s_cbranch_scc1 .LBB0_761
.Lp6f_rg7:
	s_add_u32 s98, s36, 0x58000
	s_addc_u32 s99, s37, 0
	s_add_u32 s100, s98, 0x4000
	s_addc_u32 s101, s99, 0
	v_lshlrev_b32_e32 v134, 16, v238
	v_and_b32_e32 v135, 0xffff0000, v238
	v_lshlrev_b32_e32 v136, 16, v239
	v_and_b32_e32 v137, 0xffff0000, v239
	v_lshlrev_b32_e32 v138, 16, v240
	v_and_b32_e32 v139, 0xffff0000, v240
	v_lshlrev_b32_e32 v140, 16, v241
	v_and_b32_e32 v141, 0xffff0000, v241
	v_lshlrev_b32_e32 v142, 16, v242
	v_and_b32_e32 v143, 0xffff0000, v242
	v_lshlrev_b32_e32 v144, 16, v243
	v_and_b32_e32 v145, 0xffff0000, v243
	v_lshlrev_b32_e32 v146, 16, v244
	v_and_b32_e32 v147, 0xffff0000, v244
	v_lshlrev_b32_e32 v148, 16, v245
	v_and_b32_e32 v149, 0xffff0000, v245
	v_pk_mul_f32 v[134:135], v[42:43], v[134:135]
	v_pk_mul_f32 v[136:137], v[44:45], v[136:137]
	v_pk_mul_f32 v[138:139], v[38:39], v[138:139]
	v_pk_mul_f32 v[140:141], v[40:41], v[140:141]
	v_pk_mul_f32 v[142:143], v[10:11], v[142:143]
	v_pk_mul_f32 v[144:145], v[12:13], v[144:145]
	v_pk_mul_f32 v[146:147], v[6:7], v[146:147]
	v_pk_mul_f32 v[148:149], v[8:9], v[148:149]
	v_cvt_pk_bf16_f32 v246, v134, v135
	v_cvt_pk_bf16_f32 v247, v136, v137
	v_cvt_pk_bf16_f32 v248, v138, v139
	v_cvt_pk_bf16_f32 v249, v140, v141
	v_cvt_pk_bf16_f32 v250, v142, v143
	v_cvt_pk_bf16_f32 v251, v144, v145
	v_cvt_pk_bf16_f32 v252, v146, v147
	v_cvt_pk_bf16_f32 v253, v148, v149
	ds_write_b128 v2, v[246:249]
	ds_write_b128 v2, v[250:253] offset:64
	ds_read_b128 v[150:153], v4
	ds_read_b128 v[170:173], v4 offset:1024
	s_waitcnt lgkmcnt(1)
	global_store_dwordx4 v175, v[150:153], s[98:99]
	s_waitcnt lgkmcnt(0)
	global_store_dwordx4 v175, v[170:173], s[100:101]
	s_add_i32 s41, s41, -1
	s_cmp_eq_u32 s41, 0
	s_cbranch_scc1 .LBB0_761
	s_branch .Lp6f_rg0
; #define EPI_ROWS _Pragma("unroll") for (int ai = 0; ai < 2; ++ai) _Pragma("unroll") for (int m = 0; m < 4; ++m)
;     __device__ __forceinline__ void mid(f32x4 (&acc)[2][2][4][2], const Unit& u, int wr, int wc, int fr, int fq) const {
;         asm volatile("" : "+v"(fr), "+v"(fq));
;         const int col0 = u.pn * BM + wc * 64 + fq * 8;
;         EPI_ROWS { const int row = EPI_ROW;
; #pragma unroll
;             for (int bj = 0; bj < 2; ++bj) { const size_t off = (size_t)(row >> 1) * (2 * DM) + (u.pn * 8 + wc * 2 + bj) * 64 + (row & 1) * 32 + fq * 8; f32x4 g0, g1; unpack8(*(const u32x4*)(rz + off), g0, g1);
;                 acc[ai][bj][m][0] *= g0; acc[ai][bj][m][1] *= g1; } }
;     }
.LBB0_760:
	s_lshl_b32 s0, s34, 8
	s_add_i32 s0, s0, s57
	s_lshl_b32 s0, s0, 11
	s_lshl_b32 s1, s30, 9
	s_or_b32 s1, s1, s61
	s_lshl_b32 s1, s1, 1
	s_add_u32 s0, s0, s1
	s_add_u32 s0, s8, s0
	s_addc_u32 s1, s9, 0
	v_lshrrev_b32_e32 v150, 1, v1
	v_lshlrev_b32_e32 v150, 12, v150
	v_and_b32_e32 v134, 1, v1
	v_lshl_add_u32 v150, v134, 6, v150
	v_lshl_add_u32 v150, v176, 4, v150
	s_mov_b64 s[98:99], s[0:1]
	global_load_dwordx4 v[180:183], v150, s[98:99]
	global_load_dwordx4 v[184:187], v150, s[98:99] offset:128
	s_add_u32 s98, s0, 0x8000
	s_addc_u32 s99, s1, 0
	global_load_dwordx4 v[188:191], v150, s[98:99]
	global_load_dwordx4 v[192:195], v150, s[98:99] offset:128
	s_add_u32 s98, s0, 0x10000
	s_addc_u32 s99, s1, 0
	global_load_dwordx4 v[196:199], v150, s[98:99]
	global_load_dwordx4 v[200:203], v150, s[98:99] offset:128
	s_add_u32 s98, s0, 0x18000
	s_addc_u32 s99, s1, 0
	global_load_dwordx4 v[204:207], v150, s[98:99]
	global_load_dwordx4 v[208:211], v150, s[98:99] offset:128
	s_add_u32 s98, s0, 0x40000
	s_addc_u32 s99, s1, 0
	global_load_dwordx4 v[212:215], v150, s[98:99]
	global_load_dwordx4 v[216:219], v150, s[98:99] offset:128
	s_add_u32 s98, s0, 0x48000
	s_addc_u32 s99, s1, 0
	global_load_dwordx4 v[222:225], v150, s[98:99]
	global_load_dwordx4 v[226:229], v150, s[98:99] offset:128
	s_add_u32 s98, s0, 0x50000
	s_addc_u32 s99, s1, 0
	global_load_dwordx4 v[230:233], v150, s[98:99]
	global_load_dwordx4 v[234:237], v150, s[98:99] offset:128
	s_add_u32 s98, s0, 0x58000
	s_addc_u32 s99, s1, 0
	global_load_dwordx4 v[238:241], v150, s[98:99]
	global_load_dwordx4 v[242:245], v150, s[98:99] offset:128
	s_waitcnt vmcnt(14)
	v_lshlrev_b32_e32 v134, 16, v180
	v_and_b32_e32 v135, 0xffff0000, v180
	v_lshlrev_b32_e32 v136, 16, v181
	v_and_b32_e32 v137, 0xffff0000, v181
	v_lshlrev_b32_e32 v138, 16, v182
	v_and_b32_e32 v139, 0xffff0000, v182
	v_lshlrev_b32_e32 v140, 16, v183
	v_and_b32_e32 v141, 0xffff0000, v183
	v_lshlrev_b32_e32 v142, 16, v184
	v_and_b32_e32 v143, 0xffff0000, v184
	v_lshlrev_b32_e32 v144, 16, v185
	v_and_b32_e32 v145, 0xffff0000, v185
	v_lshlrev_b32_e32 v146, 16, v186
	v_and_b32_e32 v147, 0xffff0000, v186
	v_lshlrev_b32_e32 v148, 16, v187
	v_and_b32_e32 v149, 0xffff0000, v187
	v_pk_mul_f32 v[130:131], v[130:131], v[134:135]
	v_pk_mul_f32 v[132:133], v[132:133], v[136:137]
	v_pk_mul_f32 v[126:127], v[126:127], v[138:139]
	v_pk_mul_f32 v[128:129], v[128:129], v[140:141]
	v_pk_mul_f32 v[98:99], v[98:99], v[142:143]
	v_pk_mul_f32 v[100:101], v[100:101], v[144:145]
	v_pk_mul_f32 v[94:95], v[94:95], v[146:147]
	v_pk_mul_f32 v[96:97], v[96:97], v[148:149]
	s_waitcnt vmcnt(12)
	v_lshlrev_b32_e32 v134, 16, v188
	v_and_b32_e32 v135, 0xffff0000, v188
	v_lshlrev_b32_e32 v136, 16, v189
	v_and_b32_e32 v137, 0xffff0000, v189
	v_lshlrev_b32_e32 v138, 16, v190
	v_and_b32_e32 v139, 0xffff0000, v190
	v_lshlrev_b32_e32 v140, 16, v191
	v_and_b32_e32 v141, 0xffff0000, v191
	v_lshlrev_b32_e32 v142, 16, v192
	v_and_b32_e32 v143, 0xffff0000, v192
	v_lshlrev_b32_e32 v144, 16, v193
	v_and_b32_e32 v145, 0xffff0000, v193
	v_lshlrev_b32_e32 v146, 16, v194
	v_and_b32_e32 v147, 0xffff0000, v194
	v_lshlrev_b32_e32 v148, 16, v195
	v_and_b32_e32 v149, 0xffff0000, v195
	v_pk_mul_f32 v[122:123], v[122:123], v[134:135]
	v_pk_mul_f32 v[124:125], v[124:125], v[136:137]
	v_pk_mul_f32 v[118:119], v[118:119], v[138:139]
	v_pk_mul_f32 v[120:121], v[120:121], v[140:141]
	v_pk_mul_f32 v[90:91], v[90:91], v[142:143]
	v_pk_mul_f32 v[92:93], v[92:93], v[144:145]
	v_pk_mul_f32 v[86:87], v[86:87], v[146:147]
	v_pk_mul_f32 v[88:89], v[88:89], v[148:149]
	s_waitcnt vmcnt(10)
	v_lshlrev_b32_e32 v134, 16, v196
	v_and_b32_e32 v135, 0xffff0000, v196
	v_lshlrev_b32_e32 v136, 16, v197
	v_and_b32_e32 v137, 0xffff0000, v197
	v_lshlrev_b32_e32 v138, 16, v198
	v_and_b32_e32 v139, 0xffff0000, v198
	v_lshlrev_b32_e32 v140, 16, v199
	v_and_b32_e32 v141, 0xffff0000, v199
	v_lshlrev_b32_e32 v142, 16, v200
	v_and_b32_e32 v143, 0xffff0000, v200
	v_lshlrev_b32_e32 v144, 16, v201
	v_and_b32_e32 v145, 0xffff0000, v201
	v_lshlrev_b32_e32 v146, 16, v202
	v_and_b32_e32 v147, 0xffff0000, v202
	v_lshlrev_b32_e32 v148, 16, v203
	v_and_b32_e32 v149, 0xffff0000, v203
	v_pk_mul_f32 v[114:115], v[114:115], v[134:135]
	v_pk_mul_f32 v[116:117], v[116:117], v[136:137]
	v_pk_mul_f32 v[110:111], v[110:111], v[138:139]
	v_pk_mul_f32 v[112:113], v[112:113], v[140:141]
	v_pk_mul_f32 v[82:83], v[82:83], v[142:143]
	v_pk_mul_f32 v[84:85], v[84:85], v[144:145]
	v_pk_mul_f32 v[78:79], v[78:79], v[146:147]
	v_pk_mul_f32 v[80:81], v[80:81], v[148:149]
	s_waitcnt vmcnt(8)
; #define EPI_ROWS _Pragma("unroll") for (int ai = 0; ai < 2; ++ai) _Pragma("unroll") for (int m = 0; m < 4; ++m)
;     __device__ __forceinline__ void mid(f32x4 (&acc)[2][2][4][2], const Unit& u, int wr, int wc, int fr, int fq) const {
;         asm volatile("" : "+v"(fr), "+v"(fq));
;         const int col0 = u.pn * BM + wc * 64 + fq * 8;
;         EPI_ROWS { const int row = EPI_ROW;
; #pragma unroll
;             for (int bj = 0; bj < 2; ++bj) { const size_t off = (size_t)(row >> 1) * (2 * DM) + (u.pn * 8 + wc * 2 + bj) * 64 + (row & 1) * 32 + fq * 8; f32x4 g0, g1; unpack8(*(const u32x4*)(rz + off), g0, g1);
;                 acc[ai][bj][m][0] *= g0; acc[ai][bj][m][1] *= g1; } }
;     }
	v_lshlrev_b32_e32 v134, 16, v204
	v_and_b32_e32 v135, 0xffff0000, v204
	v_lshlrev_b32_e32 v136, 16, v205
	v_and_b32_e32 v137, 0xffff0000, v205
	v_lshlrev_b32_e32 v138, 16, v206
	v_and_b32_e32 v139, 0xffff0000, v206
	v_lshlrev_b32_e32 v140, 16, v207
	v_and_b32_e32 v141, 0xffff0000, v207
	v_lshlrev_b32_e32 v142, 16, v208
	v_and_b32_e32 v143, 0xffff0000, v208
	v_lshlrev_b32_e32 v144, 16, v209
	v_and_b32_e32 v145, 0xffff0000, v209
	v_lshlrev_b32_e32 v146, 16, v210
	v_and_b32_e32 v147, 0xffff0000, v210
	v_lshlrev_b32_e32 v148, 16, v211
	v_and_b32_e32 v149, 0xffff0000, v211
	v_pk_mul_f32 v[106:107], v[106:107], v[134:135]
	v_pk_mul_f32 v[108:109], v[108:109], v[136:137]
	v_pk_mul_f32 v[102:103], v[102:103], v[138:139]
	v_pk_mul_f32 v[104:105], v[104:105], v[140:141]
	v_pk_mul_f32 v[74:75], v[74:75], v[142:143]
	v_pk_mul_f32 v[76:77], v[76:77], v[144:145]
	v_pk_mul_f32 v[70:71], v[70:71], v[146:147]
	v_pk_mul_f32 v[72:73], v[72:73], v[148:149]
	s_waitcnt vmcnt(6)
	v_lshlrev_b32_e32 v134, 16, v212
	v_and_b32_e32 v135, 0xffff0000, v212
	v_lshlrev_b32_e32 v136, 16, v213
	v_and_b32_e32 v137, 0xffff0000, v213
	v_lshlrev_b32_e32 v138, 16, v214
	v_and_b32_e32 v139, 0xffff0000, v214
	v_lshlrev_b32_e32 v140, 16, v215
	v_and_b32_e32 v141, 0xffff0000, v215
	v_lshlrev_b32_e32 v142, 16, v216
	v_and_b32_e32 v143, 0xffff0000, v216
	v_lshlrev_b32_e32 v144, 16, v217
	v_and_b32_e32 v145, 0xffff0000, v217
	v_lshlrev_b32_e32 v146, 16, v218
	v_and_b32_e32 v147, 0xffff0000, v218
	v_lshlrev_b32_e32 v148, 16, v219
	v_and_b32_e32 v149, 0xffff0000, v219
	v_pk_mul_f32 v[66:67], v[66:67], v[134:135]
	v_pk_mul_f32 v[68:69], v[68:69], v[136:137]
	v_pk_mul_f32 v[62:63], v[62:63], v[138:139]
	v_pk_mul_f32 v[64:65], v[64:65], v[140:141]
	v_pk_mul_f32 v[34:35], v[34:35], v[142:143]
	v_pk_mul_f32 v[36:37], v[36:37], v[144:145]
	v_pk_mul_f32 v[30:31], v[30:31], v[146:147]
	v_pk_mul_f32 v[32:33], v[32:33], v[148:149]
	s_waitcnt vmcnt(4)
	v_lshlrev_b32_e32 v134, 16, v222
	v_and_b32_e32 v135, 0xffff0000, v222
	v_lshlrev_b32_e32 v136, 16, v223
	v_and_b32_e32 v137, 0xffff0000, v223
	v_lshlrev_b32_e32 v138, 16, v224
	v_and_b32_e32 v139, 0xffff0000, v224
	v_lshlrev_b32_e32 v140, 16, v225
	v_and_b32_e32 v141, 0xffff0000, v225
	v_lshlrev_b32_e32 v142, 16, v226
	v_and_b32_e32 v143, 0xffff0000, v226
	v_lshlrev_b32_e32 v144, 16, v227
	v_and_b32_e32 v145, 0xffff0000, v227
	v_lshlrev_b32_e32 v146, 16, v228
	v_and_b32_e32 v147, 0xffff0000, v228
	v_lshlrev_b32_e32 v148, 16, v229
	v_and_b32_e32 v149, 0xffff0000, v229
	v_pk_mul_f32 v[58:59], v[58:59], v[134:135]
	v_pk_mul_f32 v[60:61], v[60:61], v[136:137]
	v_pk_mul_f32 v[54:55], v[54:55], v[138:139]
	v_pk_mul_f32 v[56:57], v[56:57], v[140:141]
	v_pk_mul_f32 v[26:27], v[26:27], v[142:143]
	v_pk_mul_f32 v[28:29], v[28:29], v[144:145]
	v_pk_mul_f32 v[22:23], v[22:23], v[146:147]
	v_pk_mul_f32 v[24:25], v[24:25], v[148:149]
	s_waitcnt vmcnt(2)
	v_lshlrev_b32_e32 v134, 16, v230
	v_and_b32_e32 v135, 0xffff0000, v230
	v_lshlrev_b32_e32 v136, 16, v231
	v_and_b32_e32 v137, 0xffff0000, v231
	v_lshlrev_b32_e32 v138, 16, v232
	v_and_b32_e32 v139, 0xffff0000, v232
	v_lshlrev_b32_e32 v140, 16, v233
	v_and_b32_e32 v141, 0xffff0000, v233
	v_lshlrev_b32_e32 v142, 16, v234
	v_and_b32_e32 v143, 0xffff0000, v234
	v_lshlrev_b32_e32 v144, 16, v235
	v_and_b32_e32 v145, 0xffff0000, v235
	v_lshlrev_b32_e32 v146, 16, v236
	v_and_b32_e32 v147, 0xffff0000, v236
	v_lshlrev_b32_e32 v148, 16, v237
	v_and_b32_e32 v149, 0xffff0000, v237
	v_pk_mul_f32 v[50:51], v[50:51], v[134:135]
	v_pk_mul_f32 v[52:53], v[52:53], v[136:137]
	v_pk_mul_f32 v[46:47], v[46:47], v[138:139]
	v_pk_mul_f32 v[48:49], v[48:49], v[140:141]
	v_pk_mul_f32 v[18:19], v[18:19], v[142:143]
	v_pk_mul_f32 v[20:21], v[20:21], v[144:145]
	v_pk_mul_f32 v[14:15], v[14:15], v[146:147]
	v_pk_mul_f32 v[16:17], v[16:17], v[148:149]
	s_waitcnt vmcnt(0)
	v_lshlrev_b32_e32 v134, 16, v238
	v_and_b32_e32 v135, 0xffff0000, v238
	v_lshlrev_b32_e32 v136, 16, v239
	v_and_b32_e32 v137, 0xffff0000, v239
	v_lshlrev_b32_e32 v138, 16, v240
	v_and_b32_e32 v139, 0xffff0000, v240
	v_lshlrev_b32_e32 v140, 16, v241
	v_and_b32_e32 v141, 0xffff0000, v241
	v_lshlrev_b32_e32 v142, 16, v242
	v_and_b32_e32 v143, 0xffff0000, v242
	v_lshlrev_b32_e32 v144, 16, v243
	v_and_b32_e32 v145, 0xffff0000, v243
	v_lshlrev_b32_e32 v146, 16, v244
	v_and_b32_e32 v147, 0xffff0000, v244
	v_lshlrev_b32_e32 v148, 16, v245
	v_and_b32_e32 v149, 0xffff0000, v245
	v_pk_mul_f32 v[42:43], v[42:43], v[134:135]
	v_pk_mul_f32 v[44:45], v[44:45], v[136:137]
	v_pk_mul_f32 v[38:39], v[38:39], v[138:139]
	v_pk_mul_f32 v[40:41], v[40:41], v[140:141]
	v_pk_mul_f32 v[10:11], v[10:11], v[142:143]
	v_pk_mul_f32 v[12:13], v[12:13], v[144:145]
	v_pk_mul_f32 v[6:7], v[6:7], v[146:147]
	v_pk_mul_f32 v[8:9], v[8:9], v[148:149]
